# GEMM: accumulator clear removed; first K-tile pair of each unit peeled with C=0 MFMAs
# speedup vs baseline: 1.0214x; 1.0018x over previous
; #define PG8_STAGE(bufoff, gbase, voff) do { _Pragma("unroll") for (int _i = 0; _i < 2; ++_i) \
;         __builtin_amdgcn_global_load_lds((const unsigned*)((const char*)(gbase) + (voff)[_i]), (PG8_LAS unsigned*)(lds + (bufoff) + ldsw + _i * 8192), 16, 0, 0); } while (0)
; #define PG8_LDA(dst, b, h) do { _Pragma("unroll") for (int m = 0; m < 4; ++m) _Pragma("unroll") for (int k = 0; k < 2; ++k) dst[m][k] = *(const PG8_LAS bf16x8*)(lds + PG8_SA(b, h) + aoff + m * 2048 + k * 1024); } while (0)
; #define PG8_LDB(dst, b, h) do { _Pragma("unroll") for (int n = 0; n < 2; ++n) _Pragma("unroll") for (int k = 0; k < 2; ++k) dst[n][k] = *(const PG8_LAS bf16x8*)(lds + PG8_SB(b, h) + boff + n * 2048 + k * 1024); } while (0)
; #define PG8_MMA(ai, bj, At, Bt) do { __builtin_amdgcn_s_setprio(1); _Pragma("unroll") for (int m = 0; m < 4; ++m) _Pragma("unroll") for (int n = 0; n < 2; ++n) _Pragma("unroll") for (int k = 0; k < 2; ++k) \
;         acc[ai][bj][m][n] = __builtin_amdgcn_mfma_f32_16x16x32_bf16(Bt[n][k], At[m][k], acc[ai][bj][m][n], 0, 0, 0); __builtin_amdgcn_s_setprio(0); } while (0)
; #define PG8_WAIT_V(n) asm volatile("s_waitcnt vmcnt(" #n ")" ::: "memory")
; #define PG8_WAIT_L(n) asm volatile("s_waitcnt lgkmcnt(" #n ")" ::: "memory")
; #define PG8_BAR __builtin_amdgcn_s_barrier()
; #define PG8_SCHED __builtin_amdgcn_sched_barrier(0)
; template <class Epi, class Sched, bool ALIGN_EPI = false, bool SP2 = false>
; __device__ __forceinline__ void gemm_phase(PG8_LAS unsigned char* lds, const Gemm g, const Sched& S, const Epi& E) {
;     ...
;             PG8_LDB(B0, 0, 0); PG8_LDB(B1, 0, 1); PG8_SCHED; PG8_LDA(At, 0, 0); PG8_STAGE(PG8_SA(1, 1), a1 + hstep, voffA);
;             PG8_WAIT_V(8); PG8_WAIT_L(0); PG8_BAR; PG8_MMA(0, 0, At, B0); PG8_MMA(0, 1, At, B1); PG8_BAR; PG8_SCHED;
;             PG8_LDA(At, 0, 1); PG8_STAGE(PG8_SB(0, 0), b2, voffB); PG8_STAGE(PG8_SB(0, 1), b2 + hstep, voffB); PG8_STAGE(PG8_SA(0, 0), a2, voffA);
;             PG8_WAIT_V(8); PG8_WAIT_L(0); PG8_BAR; PG8_MMA(1, 0, At, B0); PG8_MMA(1, 1, At, B1); PG8_BAR; PG8_SCHED;
;     ...
; #pragma unroll
;         for (int a = 0; a < 2; ++a)
; #pragma unroll
;             for (int b = 0; b < 2; ++b)
; #pragma unroll
;                 for (int m = 0; m < 4; ++m)
; #pragma unroll
;                     for (int n = 0; n < 2; ++n) acc[a][b][m][n] = (f32x4){0.f, 0.f, 0.f, 0.f};
.LBB0_710:
	s_add_u32 s2, s2, 0x80
	s_addc_u32 s3, s3, 0
	s_add_u32 s8, s6, 0x100
	s_addc_u32 s9, s7, 0
	s_mov_b32 s6, 0
	s_add_i32 s10, s6, 2
	s_add_u32 s11, s2, 0x80
	s_addc_u32 s7, s3, 0
	s_waitcnt lgkmcnt(0)
	s_add_i32 s52, 0, 0x10000
	v_add_u32_e32 v0, s52, v211
	ds_read_b128 v[130:133], v0
	ds_read_b128 v[134:137], v0 offset:1024
	ds_read_b128 v[138:141], v0 offset:2048
	ds_read_b128 v[142:145], v0 offset:3072
	v_add_u32_e32 v0, s87, v211
	ds_read_b128 v[146:149], v0
	ds_read_b128 v[150:153], v0 offset:1024
	ds_read_b128 v[154:157], v0 offset:2048
	ds_read_b128 v[158:161], v0 offset:3072
	s_cmp_eq_u32 s57, s6
	s_cselect_b32 s6, s48, s11
	s_cselect_b32 s7, s49, s7
	s_cselect_b32 s47, s51, s9
	s_cselect_b32 s46, s50, s8
	v_lshl_add_u64 v[208:209], s[2:3], 0, v[174:175]
	s_add_i32 m0, s23, 0xc000
	ds_read_b128 v[162:165], v214
	ds_read_b128 v[180:183], v214 offset:1024
	ds_read_b128 v[184:187], v214 offset:2048
	ds_read_b128 v[188:191], v214 offset:3072
	ds_read_b128 v[192:195], v214 offset:4096
	ds_read_b128 v[196:199], v214 offset:5120
	ds_read_b128 v[200:203], v214 offset:6144
	ds_read_b128 v[204:207], v214 offset:7168
	global_load_lds_dwordx4 v[208:209], off
	v_lshl_add_u64 v[208:209], s[2:3], 0, v[176:177]
	s_add_i32 m0, s23, 0xe000
	s_nop 0
	global_load_lds_dwordx4 v[208:209], off
	s_waitcnt vmcnt(8)
	s_waitcnt lgkmcnt(0)
	s_barrier
	s_setprio 1
	s_waitcnt lgkmcnt(0)
	v_mfma_f32_16x16x32_bf16 v[126:129], v[130:133], v[162:165], 0
	v_mfma_f32_16x16x32_bf16 v[122:125], v[138:141], v[162:165], 0
	v_mfma_f32_16x16x32_bf16 v[118:121], v[130:133], v[184:187], 0
	v_mfma_f32_16x16x32_bf16 v[110:113], v[138:141], v[184:187], 0
	v_mfma_f32_16x16x32_bf16 v[102:105], v[130:133], v[192:195], 0
	v_mfma_f32_16x16x32_bf16 v[94:97], v[138:141], v[192:195], 0
	v_mfma_f32_16x16x32_bf16 v[86:89], v[130:133], v[200:203], 0
	v_mfma_f32_16x16x32_bf16 v[78:81], v[138:141], v[200:203], 0
	v_mfma_f32_16x16x32_bf16 v[126:129], v[134:137], v[180:183], v[126:129]
	v_mfma_f32_16x16x32_bf16 v[122:125], v[142:145], v[180:183], v[122:125]
	v_mfma_f32_16x16x32_bf16 v[118:121], v[134:137], v[188:191], v[118:121]
	v_mfma_f32_16x16x32_bf16 v[110:113], v[142:145], v[188:191], v[110:113]
	v_mfma_f32_16x16x32_bf16 v[102:105], v[134:137], v[196:199], v[102:105]
	v_mfma_f32_16x16x32_bf16 v[94:97], v[142:145], v[196:199], v[94:97]
	v_mfma_f32_16x16x32_bf16 v[86:89], v[134:137], v[204:207], v[86:89]
	v_mfma_f32_16x16x32_bf16 v[78:81], v[142:145], v[204:207], v[78:81]
	s_setprio 0
	s_setprio 1
	v_mfma_f32_16x16x32_bf16 v[114:117], v[146:149], v[162:165], 0
	v_mfma_f32_16x16x32_bf16 v[106:109], v[154:157], v[162:165], 0
	v_mfma_f32_16x16x32_bf16 v[98:101], v[146:149], v[184:187], 0
	v_mfma_f32_16x16x32_bf16 v[90:93], v[154:157], v[184:187], 0
	v_mfma_f32_16x16x32_bf16 v[82:85], v[146:149], v[192:195], 0
	v_mfma_f32_16x16x32_bf16 v[74:77], v[154:157], v[192:195], 0
	v_mfma_f32_16x16x32_bf16 v[70:73], v[146:149], v[200:203], 0
	v_mfma_f32_16x16x32_bf16 v[66:69], v[154:157], v[200:203], 0
	v_mfma_f32_16x16x32_bf16 v[114:117], v[150:153], v[180:183], v[114:117]
	v_mfma_f32_16x16x32_bf16 v[106:109], v[158:161], v[180:183], v[106:109]
	v_mfma_f32_16x16x32_bf16 v[98:101], v[150:153], v[188:191], v[98:101]
	v_mfma_f32_16x16x32_bf16 v[90:93], v[158:161], v[188:191], v[90:93]
	v_mfma_f32_16x16x32_bf16 v[82:85], v[150:153], v[196:199], v[82:85]
	v_mfma_f32_16x16x32_bf16 v[74:77], v[158:161], v[196:199], v[74:77]
	v_mfma_f32_16x16x32_bf16 v[70:73], v[150:153], v[204:207], v[70:73]
	v_mfma_f32_16x16x32_bf16 v[66:69], v[158:161], v[204:207], v[66:69]
	s_setprio 0
	s_barrier
	s_add_i32 s11, s52, s22
	v_lshl_add_u64 v[208:209], s[46:47], 0, v[168:169]
	s_mov_b32 m0, s11
	ds_read_b128 v[162:165], v214 offset:16384
	ds_read_b128 v[180:183], v214 offset:17408
	ds_read_b128 v[184:187], v214 offset:18432
	ds_read_b128 v[188:191], v214 offset:19456
	ds_read_b128 v[192:195], v214 offset:20480
	ds_read_b128 v[196:199], v214 offset:21504
	ds_read_b128 v[200:203], v214 offset:22528
	ds_read_b128 v[204:207], v214 offset:23552
	global_load_lds_dwordx4 v[208:209], off
	s_add_i32 m0, s11, 0x2000
	v_lshl_add_u64 v[216:217], s[46:47], 0, v[172:173]
	s_add_u32 s46, s46, s96
	s_addc_u32 s47, s47, 0
	s_add_i32 s11, s87, s22
	global_load_lds_dwordx4 v[216:217], off
	v_lshl_add_u64 v[220:221], s[46:47], 0, v[168:169]
	s_mov_b32 m0, s11
	v_lshl_add_u64 v[224:225], s[46:47], 0, v[172:173]
	global_load_lds_dwordx4 v[220:221], off
	s_add_i32 m0, s11, 0x2000
	v_lshl_add_u64 v[228:229], s[6:7], 0, v[166:167]
	global_load_lds_dwordx4 v[224:225], off
	s_mov_b32 m0, s23
	v_lshl_add_u64 v[230:231], s[6:7], 0, v[170:171]
	global_load_lds_dwordx4 v[228:229], off
	s_mov_b32 m0, s24
	s_nop 0
	global_load_lds_dwordx4 v[230:231], off
	s_waitcnt vmcnt(8)
	s_waitcnt lgkmcnt(0)
	s_barrier
; #define PG8_STAGE(bufoff, gbase, voff) do { _Pragma("unroll") for (int _i = 0; _i < 2; ++_i) \
;         __builtin_amdgcn_global_load_lds((const unsigned*)((const char*)(gbase) + (voff)[_i]), (PG8_LAS unsigned*)(lds + (bufoff) + ldsw + _i * 8192), 16, 0, 0); } while (0)
; #define PG8_LDA(dst, b, h) do { _Pragma("unroll") for (int m = 0; m < 4; ++m) _Pragma("unroll") for (int k = 0; k < 2; ++k) dst[m][k] = *(const PG8_LAS bf16x8*)(lds + PG8_SA(b, h) + aoff + m * 2048 + k * 1024); } while (0)
; #define PG8_LDB(dst, b, h) do { _Pragma("unroll") for (int n = 0; n < 2; ++n) _Pragma("unroll") for (int k = 0; k < 2; ++k) dst[n][k] = *(const PG8_LAS bf16x8*)(lds + PG8_SB(b, h) + boff + n * 2048 + k * 1024); } while (0)
; #define PG8_MMA(ai, bj, At, Bt) do { __builtin_amdgcn_s_setprio(1); _Pragma("unroll") for (int m = 0; m < 4; ++m) _Pragma("unroll") for (int n = 0; n < 2; ++n) _Pragma("unroll") for (int k = 0; k < 2; ++k) \
;         acc[ai][bj][m][n] = __builtin_amdgcn_mfma_f32_16x16x32_bf16(Bt[n][k], At[m][k], acc[ai][bj][m][n], 0, 0, 0); __builtin_amdgcn_s_setprio(0); } while (0)
; #define PG8_WAIT_V(n) asm volatile("s_waitcnt vmcnt(" #n ")" ::: "memory")
; #define PG8_WAIT_L(n) asm volatile("s_waitcnt lgkmcnt(" #n ")" ::: "memory")
; #define PG8_BAR __builtin_amdgcn_s_barrier()
; #define PG8_SCHED __builtin_amdgcn_sched_barrier(0)
; template <class Epi, class Sched, bool ALIGN_EPI = false, bool SP2 = false>
; __device__ __forceinline__ void gemm_phase(PG8_LAS unsigned char* lds, const Gemm g, const Sched& S, const Epi& E) {
;     ...
;             PG8_WAIT_V(8); PG8_WAIT_L(0); PG8_BAR; PG8_MMA(1, 0, At, B0); PG8_MMA(1, 1, At, B1); PG8_BAR; PG8_SCHED;
;             PG8_LDB(B0, 1, 0); PG8_LDB(B1, 1, 1); PG8_SCHED; PG8_LDA(At, 1, 0); PG8_STAGE(PG8_SA(0, 1), a2 + hstep, voffA);
;             PG8_WAIT_V(8); PG8_WAIT_L(0); PG8_BAR; PG8_MMA(0, 0, At, B0); PG8_MMA(0, 1, At, B1); PG8_BAR; PG8_SCHED;
	s_setprio 1
	s_waitcnt lgkmcnt(0)
	v_mfma_f32_16x16x32_bf16 v[62:65], v[130:133], v[162:165], 0
	v_mfma_f32_16x16x32_bf16 v[58:61], v[138:141], v[162:165], 0
	v_mfma_f32_16x16x32_bf16 v[54:57], v[130:133], v[184:187], 0
	v_mfma_f32_16x16x32_bf16 v[46:49], v[138:141], v[184:187], 0
	v_mfma_f32_16x16x32_bf16 v[38:41], v[130:133], v[192:195], 0
	v_mfma_f32_16x16x32_bf16 v[30:33], v[138:141], v[192:195], 0
	v_mfma_f32_16x16x32_bf16 v[22:25], v[130:133], v[200:203], 0
	v_mfma_f32_16x16x32_bf16 v[14:17], v[138:141], v[200:203], 0
	v_mfma_f32_16x16x32_bf16 v[62:65], v[134:137], v[180:183], v[62:65]
	v_mfma_f32_16x16x32_bf16 v[58:61], v[142:145], v[180:183], v[58:61]
	v_mfma_f32_16x16x32_bf16 v[54:57], v[134:137], v[188:191], v[54:57]
	v_mfma_f32_16x16x32_bf16 v[46:49], v[142:145], v[188:191], v[46:49]
	v_mfma_f32_16x16x32_bf16 v[38:41], v[134:137], v[196:199], v[38:41]
	v_mfma_f32_16x16x32_bf16 v[30:33], v[142:145], v[196:199], v[30:33]
	v_mfma_f32_16x16x32_bf16 v[22:25], v[134:137], v[204:207], v[22:25]
	v_mfma_f32_16x16x32_bf16 v[14:17], v[142:145], v[204:207], v[14:17]
	s_setprio 0
	s_setprio 1
	v_mfma_f32_16x16x32_bf16 v[50:53], v[146:149], v[162:165], 0
	v_mfma_f32_16x16x32_bf16 v[42:45], v[154:157], v[162:165], 0
	v_mfma_f32_16x16x32_bf16 v[34:37], v[146:149], v[184:187], 0
	v_mfma_f32_16x16x32_bf16 v[26:29], v[154:157], v[184:187], 0
	v_mfma_f32_16x16x32_bf16 v[18:21], v[146:149], v[192:195], 0
	v_mfma_f32_16x16x32_bf16 v[10:13], v[154:157], v[192:195], 0
	v_mfma_f32_16x16x32_bf16 v[6:9], v[146:149], v[200:203], 0
	v_mfma_f32_16x16x32_bf16 v[2:5], v[154:157], v[200:203], 0
	v_mfma_f32_16x16x32_bf16 v[50:53], v[150:153], v[180:183], v[50:53]
	v_mfma_f32_16x16x32_bf16 v[42:45], v[158:161], v[180:183], v[42:45]
	v_mfma_f32_16x16x32_bf16 v[34:37], v[150:153], v[188:191], v[34:37]
	v_mfma_f32_16x16x32_bf16 v[26:29], v[158:161], v[188:191], v[26:29]
	v_mfma_f32_16x16x32_bf16 v[18:21], v[150:153], v[196:199], v[18:21]
	v_mfma_f32_16x16x32_bf16 v[10:13], v[158:161], v[196:199], v[10:13]
	v_mfma_f32_16x16x32_bf16 v[6:9], v[150:153], v[204:207], v[6:9]
	v_mfma_f32_16x16x32_bf16 v[2:5], v[158:161], v[204:207], v[2:5]
	s_setprio 0
	s_barrier
	s_add_i32 s11, 0, 0x18000
	v_add_u32_e32 v0, s11, v211
	ds_read_b128 v[130:133], v0
	ds_read_b128 v[134:137], v0 offset:1024
	ds_read_b128 v[138:141], v0 offset:2048
	ds_read_b128 v[142:145], v0 offset:3072
	v_add_u32_e32 v0, s86, v211
	ds_read_b128 v[146:149], v0
	ds_read_b128 v[150:153], v0 offset:1024
	ds_read_b128 v[154:157], v0 offset:2048
	ds_read_b128 v[158:161], v0 offset:3072
	s_add_u32 s6, s6, s96
	s_addc_u32 s7, s7, 0
	s_mov_b32 m0, s25
	v_lshl_add_u64 v[238:239], s[6:7], 0, v[166:167]
	ds_read_b128 v[162:165], v214 offset:32768
	ds_read_b128 v[180:183], v214 offset:33792
	ds_read_b128 v[184:187], v214 offset:34816
	ds_read_b128 v[188:191], v214 offset:35840
	ds_read_b128 v[192:195], v214 offset:36864
	ds_read_b128 v[196:199], v214 offset:37888
	ds_read_b128 v[200:203], v214 offset:38912
	ds_read_b128 v[204:207], v214 offset:39936
	global_load_lds_dwordx4 v[238:239], off
	v_lshl_add_u64 v[238:239], s[6:7], 0, v[170:171]
	s_mov_b32 m0, s27
	s_nop 0
	global_load_lds_dwordx4 v[238:239], off
	s_waitcnt vmcnt(8)
	s_waitcnt lgkmcnt(0)
	s_barrier
	s_setprio 1
	s_waitcnt lgkmcnt(0)
	v_mfma_f32_16x16x32_bf16 v[126:129], v[130:133], v[162:165], v[126:129]
	v_mfma_f32_16x16x32_bf16 v[122:125], v[138:141], v[162:165], v[122:125]
	v_mfma_f32_16x16x32_bf16 v[118:121], v[130:133], v[184:187], v[118:121]
	v_mfma_f32_16x16x32_bf16 v[110:113], v[138:141], v[184:187], v[110:113]
	v_mfma_f32_16x16x32_bf16 v[102:105], v[130:133], v[192:195], v[102:105]
	v_mfma_f32_16x16x32_bf16 v[94:97], v[138:141], v[192:195], v[94:97]
	v_mfma_f32_16x16x32_bf16 v[86:89], v[130:133], v[200:203], v[86:89]
	v_mfma_f32_16x16x32_bf16 v[78:81], v[138:141], v[200:203], v[78:81]
	v_mfma_f32_16x16x32_bf16 v[126:129], v[134:137], v[180:183], v[126:129]
	v_mfma_f32_16x16x32_bf16 v[122:125], v[142:145], v[180:183], v[122:125]
	v_mfma_f32_16x16x32_bf16 v[118:121], v[134:137], v[188:191], v[118:121]
	v_mfma_f32_16x16x32_bf16 v[110:113], v[142:145], v[188:191], v[110:113]
	v_mfma_f32_16x16x32_bf16 v[102:105], v[134:137], v[196:199], v[102:105]
	v_mfma_f32_16x16x32_bf16 v[94:97], v[142:145], v[196:199], v[94:97]
	v_mfma_f32_16x16x32_bf16 v[86:89], v[134:137], v[204:207], v[86:89]
	v_mfma_f32_16x16x32_bf16 v[78:81], v[142:145], v[204:207], v[78:81]
	s_setprio 0
	s_setprio 1
	v_mfma_f32_16x16x32_bf16 v[114:117], v[146:149], v[162:165], v[114:117]
	v_mfma_f32_16x16x32_bf16 v[106:109], v[154:157], v[162:165], v[106:109]
	v_mfma_f32_16x16x32_bf16 v[98:101], v[146:149], v[184:187], v[98:101]
	v_mfma_f32_16x16x32_bf16 v[90:93], v[154:157], v[184:187], v[90:93]
	v_mfma_f32_16x16x32_bf16 v[82:85], v[146:149], v[192:195], v[82:85]
	v_mfma_f32_16x16x32_bf16 v[74:77], v[154:157], v[192:195], v[74:77]
	v_mfma_f32_16x16x32_bf16 v[70:73], v[146:149], v[200:203], v[70:73]
	v_mfma_f32_16x16x32_bf16 v[66:69], v[154:157], v[200:203], v[66:69]
	v_mfma_f32_16x16x32_bf16 v[114:117], v[150:153], v[180:183], v[114:117]
	v_mfma_f32_16x16x32_bf16 v[106:109], v[158:161], v[180:183], v[106:109]
	v_mfma_f32_16x16x32_bf16 v[98:101], v[150:153], v[188:191], v[98:101]
	v_mfma_f32_16x16x32_bf16 v[90:93], v[158:161], v[188:191], v[90:93]
	v_mfma_f32_16x16x32_bf16 v[82:85], v[150:153], v[196:199], v[82:85]
	v_mfma_f32_16x16x32_bf16 v[74:77], v[158:161], v[196:199], v[74:77]
	v_mfma_f32_16x16x32_bf16 v[70:73], v[150:153], v[204:207], v[70:73]
	v_mfma_f32_16x16x32_bf16 v[66:69], v[158:161], v[204:207], v[66:69]
	s_setprio 0
	s_barrier
; #define PG8_STAGE(bufoff, gbase, voff) do { _Pragma("unroll") for (int _i = 0; _i < 2; ++_i) \
;         __builtin_amdgcn_global_load_lds((const unsigned*)((const char*)(gbase) + (voff)[_i]), (PG8_LAS unsigned*)(lds + (bufoff) + ldsw + _i * 8192), 16, 0, 0); } while (0)
; #define PG8_LDA(dst, b, h) do { _Pragma("unroll") for (int m = 0; m < 4; ++m) _Pragma("unroll") for (int k = 0; k < 2; ++k) dst[m][k] = *(const PG8_LAS bf16x8*)(lds + PG8_SA(b, h) + aoff + m * 2048 + k * 1024); } while (0)
; #define PG8_MMA(ai, bj, At, Bt) do { __builtin_amdgcn_s_setprio(1); _Pragma("unroll") for (int m = 0; m < 4; ++m) _Pragma("unroll") for (int n = 0; n < 2; ++n) _Pragma("unroll") for (int k = 0; k < 2; ++k) \
;         acc[ai][bj][m][n] = __builtin_amdgcn_mfma_f32_16x16x32_bf16(Bt[n][k], At[m][k], acc[ai][bj][m][n], 0, 0, 0); __builtin_amdgcn_s_setprio(0); } while (0)
; #define PG8_WAIT_V(n) asm volatile("s_waitcnt vmcnt(" #n ")" ::: "memory")
; #define PG8_WAIT_L(n) asm volatile("s_waitcnt lgkmcnt(" #n ")" ::: "memory")
; #define PG8_BAR __builtin_amdgcn_s_barrier()
; #define PG8_SCHED __builtin_amdgcn_sched_barrier(0)
; template <class Epi, class Sched, bool ALIGN_EPI = false, bool SP2 = false>
; __device__ __forceinline__ void gemm_phase(PG8_LAS unsigned char* lds, const Gemm g, const Sched& S, const Epi& E) {
;     ...
;         for (int t = 0; t < nt; t += 2) {
;             const bool last = (t == nt - 2);
;             const char* a1 = cA + (size_t)(t + 1) * kstep;
;             const char* a2 = last ? nA : cA + (size_t)(t + 2) * kstep; const char* b2 = last ? nB : cB + (size_t)(t + 2) * kstep;
;             const char* a3 = a2 + kstep; const char* b3 = b2 + kstep;
;     ...
;             PG8_LDA(At, 1, 1); PG8_STAGE(PG8_SB(1, 0), b3, voffB); PG8_STAGE(PG8_SB(1, 1), b3 + hstep, voffB); PG8_STAGE(PG8_SA(1, 0), a3, voffA);
;             PG8_WAIT_V(8); PG8_WAIT_L(0); PG8_BAR; PG8_MMA(1, 0, At, B0); PG8_MMA(1, 1, At, B1); PG8_BAR; PG8_SCHED;
	s_add_i32 s6, s11, s22
	v_lshl_add_u64 v[208:209], v[208:209], 0, s[12:13]
	s_mov_b32 m0, s6
	ds_read_b128 v[162:165], v214 offset:49152
	ds_read_b128 v[180:183], v214 offset:50176
	ds_read_b128 v[184:187], v214 offset:51200
	ds_read_b128 v[188:191], v214 offset:52224
	ds_read_b128 v[192:195], v214 offset:53248
	ds_read_b128 v[196:199], v214 offset:54272
	ds_read_b128 v[200:203], v214 offset:55296
	ds_read_b128 v[204:207], v214 offset:56320
	global_load_lds_dwordx4 v[208:209], off
	v_lshl_add_u64 v[208:209], v[216:217], 0, s[12:13]
	s_add_i32 m0, s6, 0x2000
	s_add_i32 s6, s86, s22
	global_load_lds_dwordx4 v[208:209], off
	v_lshl_add_u64 v[208:209], v[220:221], 0, s[12:13]
	s_mov_b32 m0, s6
	s_nop 0
	global_load_lds_dwordx4 v[208:209], off
	v_lshl_add_u64 v[208:209], v[224:225], 0, s[12:13]
	s_add_i32 m0, s6, 0x2000
	s_nop 0
	global_load_lds_dwordx4 v[208:209], off
	v_lshl_add_u64 v[208:209], v[228:229], 0, s[12:13]
	s_mov_b32 m0, s54
	s_nop 0
	global_load_lds_dwordx4 v[208:209], off
	v_lshl_add_u64 v[208:209], v[230:231], 0, s[12:13]
	s_mov_b32 m0, s55
	s_nop 0
	global_load_lds_dwordx4 v[208:209], off
	s_waitcnt vmcnt(8)
	s_waitcnt lgkmcnt(0)
	s_barrier
	s_setprio 1
	s_waitcnt lgkmcnt(0)
	v_mfma_f32_16x16x32_bf16 v[62:65], v[130:133], v[162:165], v[62:65]
	v_mfma_f32_16x16x32_bf16 v[58:61], v[138:141], v[162:165], v[58:61]
	v_mfma_f32_16x16x32_bf16 v[54:57], v[130:133], v[184:187], v[54:57]
	v_mfma_f32_16x16x32_bf16 v[46:49], v[138:141], v[184:187], v[46:49]
	v_mfma_f32_16x16x32_bf16 v[38:41], v[130:133], v[192:195], v[38:41]
	v_mfma_f32_16x16x32_bf16 v[30:33], v[138:141], v[192:195], v[30:33]
	v_mfma_f32_16x16x32_bf16 v[22:25], v[130:133], v[200:203], v[22:25]
	v_mfma_f32_16x16x32_bf16 v[14:17], v[138:141], v[200:203], v[14:17]
	v_mfma_f32_16x16x32_bf16 v[62:65], v[134:137], v[180:183], v[62:65]
	v_mfma_f32_16x16x32_bf16 v[58:61], v[142:145], v[180:183], v[58:61]
	v_mfma_f32_16x16x32_bf16 v[54:57], v[134:137], v[188:191], v[54:57]
	v_mfma_f32_16x16x32_bf16 v[46:49], v[142:145], v[188:191], v[46:49]
	v_mfma_f32_16x16x32_bf16 v[38:41], v[134:137], v[196:199], v[38:41]
	v_mfma_f32_16x16x32_bf16 v[30:33], v[142:145], v[196:199], v[30:33]
	v_mfma_f32_16x16x32_bf16 v[22:25], v[134:137], v[204:207], v[22:25]
	v_mfma_f32_16x16x32_bf16 v[14:17], v[142:145], v[204:207], v[14:17]
	s_setprio 0
	s_setprio 1
	v_mfma_f32_16x16x32_bf16 v[50:53], v[146:149], v[162:165], v[50:53]
	v_mfma_f32_16x16x32_bf16 v[42:45], v[154:157], v[162:165], v[42:45]
	v_mfma_f32_16x16x32_bf16 v[34:37], v[146:149], v[184:187], v[34:37]
	v_mfma_f32_16x16x32_bf16 v[26:29], v[154:157], v[184:187], v[26:29]
	v_mfma_f32_16x16x32_bf16 v[18:21], v[146:149], v[192:195], v[18:21]
	v_mfma_f32_16x16x32_bf16 v[10:13], v[154:157], v[192:195], v[10:13]
	v_mfma_f32_16x16x32_bf16 v[6:9], v[146:149], v[200:203], v[6:9]
	v_mfma_f32_16x16x32_bf16 v[2:5], v[154:157], v[200:203], v[2:5]
	v_mfma_f32_16x16x32_bf16 v[50:53], v[150:153], v[180:183], v[50:53]
	v_mfma_f32_16x16x32_bf16 v[42:45], v[158:161], v[180:183], v[42:45]
	v_mfma_f32_16x16x32_bf16 v[34:37], v[150:153], v[188:191], v[34:37]
	v_mfma_f32_16x16x32_bf16 v[26:29], v[158:161], v[188:191], v[26:29]
	v_mfma_f32_16x16x32_bf16 v[18:21], v[150:153], v[196:199], v[18:21]
	v_mfma_f32_16x16x32_bf16 v[10:13], v[158:161], v[196:199], v[10:13]
	v_mfma_f32_16x16x32_bf16 v[6:9], v[150:153], v[204:207], v[6:9]
	v_mfma_f32_16x16x32_bf16 v[2:5], v[158:161], v[204:207], v[2:5]
	s_setprio 0
	s_barrier
	s_add_u32 s2, s2, 0x100
	s_addc_u32 s3, s3, 0
	s_add_u32 s8, s8, 0x100
	s_addc_u32 s9, s9, 0
	s_cmp_ge_u32 s10, s56
	s_mov_b32 s6, s10
	s_cbranch_scc0 .LBB0_711
	s_branch .Lk_exit

; #define PG8_BAR __builtin_amdgcn_s_barrier()
; template <class Epi, class Sched, bool ALIGN_EPI = false, bool SP2 = false>
; __device__ __forceinline__ void gemm_phase(PG8_LAS unsigned char* lds, const Gemm g, const Sched& S, const Epi& E) {
;     ...
;         if constexpr (ALIGN_EPI) { if (wr == 0) PG8_BAR; }
;         if constexpr (!Epi::AFTER_DRAIN) { E(acc, cur, wr, wc, fr, fq); S.done(cur); }
.Lk_exit:
	s_and_b64 vcc, exec, s[40:41]
	s_cbranch_vccz .LBB0_714
	s_barrier
